# v042 g1 even layers: CUs 232-255 convert w_down[0] part / layer-3 gate/up leftovers during the phase
# speedup vs baseline: 1.0096x; 1.0055x over previous
; DEV void phase_prologue_a(const Frame& F0) {
;     ...
;         constexpr int GU_NB = 2 * FF / 32, GU_ITEMS = 16 * GU_NB;
;         for (int it = F.gw; it < NE * GU_ITEMS; it += F.NGW) { const int e = it / GU_ITEMS, r = it % GU_ITEMS, kb = r / GU_NB, nb = r % GU_NB; const int d0 = 32 * nb, j = d0 >> 8, w = d0 & 255;
;             const float* src = (w < 128 ? GIN(I_WGATE) : GIN(I_WUP)) + ((size_t)l * NE + e) * 1024 * FF;
;             tr_item(src, FF, 128 * j + (w & 127), 64 * kb, (bf16_t*)(F.ws + WS_WGU) + ((size_t)l * NE + e) * 2 * FF * 1024, 1024, d0, scr, F.lane); }
.LBB0_24:
	s_andn2_b64 vcc, exec, s[10:11]
	s_cbranch_vccnz .LBB0_29
	s_lshl_b64 s[20:21], s[2:3], 27
	s_mov_b32 s28, s31
	s_cmp_eq_u32 s14, 0
	s_cbranch_scc1 .Lpro_gu_all
	v_readlane_b32 s100, v255, 51
	s_cmp_lg_u32 s100, 0x100
	s_cbranch_scc1 .Lpro_gu_all
	s_cmp_eq_u32 s14, 1
	s_cbranch_scc1 .LBB0_29
	s_cmp_lg_u32 s14, 0
	s_cbranch_scc1 .LBB0_29

; #define LAS __attribute__((address_space(3)))
; #define NT_LOAD(p) __builtin_nontemporal_load(p)
; DEV void tr_item(const float* W, int ldw, int col0, int k0, bf16_t* WT, int K, int row0, LAS float* scr, int lane) {
; #pragma unroll 8
;     for (int i = 0; i < 32; ++i) { const int kk = 2 * i + (lane >> 5); scr[kk * 33 + (lane & 31)] = NT_LOAD(&W[(size_t)(k0 + kk) * ldw + col0 + (lane & 31)]); }
; DEV void phase_prologue_a(const Frame& F0) {
;     ...
;         constexpr int D_ITEMS = (FF / 64) * 32;
;         for (int it = F.gw; it < NE * D_ITEMS; it += F.NGW) { const int e = it / D_ITEMS, r = it % D_ITEMS, kb = r / 32, nb = r % 32;
;             tr_item(GIN(I_WDOWN) + ((size_t)l * NE + e) * FF * 1024, 1024, 32 * nb, 64 * kb, (bf16_t*)(F.ws + WS_WD) + ((size_t)l * NE + e) * 1024 * FF, FF, 32 * nb, scr, F.lane); }
.Lpro_dn_do:
	s_lshl_b64 s[20:21], s[2:3], 4
	s_mov_b32 s2, s31
	v_readlane_b32 s100, v255, 51
	s_cmp_lg_u32 s100, 0x100
	s_cbranch_scc1 .Lpro_dn_all
	s_cmp_lg_u32 s14, 0
	s_cbranch_scc1 .Lpro_dn_all
	s_add_i32 s2, s2, 0x1e00
.Lpro_dn_all:
	s_mov_b64 s[40:41], 0x10000
	s_mov_b64 s[42:43], 0x8000
	v_add_u32_e32 v100, 0x400, v42
	v_add_u32_e32 v101, 0x840, v42
	v_add_u32_e32 v102, 0xc40, v42
	v_add_u32_e32 v103, 0x1080, v42
	v_add_u32_e32 v104, 0x1480, v42
	v_add_u32_e32 v105, 0x18c0, v42
	v_add_u32_e32 v106, 0x1cc0, v42
	s_ashr_i32 s22, s2, 31
	s_lshr_b32 s22, s22, 22
	s_add_i32 s22, s2, s22
	s_ashr_i32 s24, s22, 10
	s_and_b32 s22, s22, 0xfc00
	s_sub_i32 s22, s2, s22
	s_sext_i32_i16 s23, s22
	s_bfe_u32 s23, s23, 0x5001a
	s_add_i32 s23, s22, s23
	s_sext_i32_i16 s26, s23
	s_and_b32 s23, s23, 0xffe0
	s_sub_i32 s22, s22, s23
	s_sext_i32_i16 s22, s22
	s_lshl_b32 s22, s22, 5
	s_lshl_b32 s23, s26, 1
	s_ashr_i32 s25, s24, 31
	s_and_b32 s26, s23, 0xffffffc0
	s_ashr_i32 s23, s22, 31
	s_lshl_b64 s[28:29], s[24:25], 23
	s_lshl_b64 s[38:39], s[22:23], 2
	s_add_u32 s28, s38, s28
	v_add_u32_e32 v22, s26, v45
	s_addc_u32 s29, s39, s29
	v_add_u32_e32 v24, s26, v46
	v_add_u32_e32 v26, s26, v47
	v_add_u32_e32 v28, s26, v48
	v_add_u32_e32 v30, s26, v49
	v_add_u32_e32 v32, s26, v43
	v_add_u32_e32 v34, s26, v44
	s_ashr_i32 s27, s26, 31
	v_ashrrev_i32_e32 v23, 31, v22
	v_ashrrev_i32_e32 v25, 31, v24
	v_ashrrev_i32_e32 v27, 31, v26
	v_ashrrev_i32_e32 v29, 31, v28
	v_ashrrev_i32_e32 v31, 31, v30
	v_ashrrev_i32_e32 v33, 31, v32
	v_ashrrev_i32_e32 v35, 31, v34
	v_lshl_add_u64 v[36:37], v[2:3], 0, s[26:27]
	v_lshlrev_b64 v[22:23], 12, v[22:23]
	v_lshlrev_b64 v[24:25], 12, v[24:25]
	v_lshlrev_b64 v[26:27], 12, v[26:27]
	v_lshlrev_b64 v[28:29], 12, v[28:29]
	v_lshlrev_b64 v[30:31], 12, v[30:31]
	v_lshlrev_b64 v[32:33], 12, v[32:33]
	v_lshlrev_b64 v[34:35], 12, v[34:35]
	v_lshlrev_b64 v[36:37], 12, v[36:37]
	v_lshl_add_u64 v[22:23], s[28:29], 0, v[22:23]
	v_lshl_add_u64 v[24:25], s[28:29], 0, v[24:25]
	v_lshl_add_u64 v[26:27], s[28:29], 0, v[26:27]
	v_lshl_add_u64 v[28:29], s[28:29], 0, v[28:29]
	v_lshl_add_u64 v[30:31], s[28:29], 0, v[30:31]
	v_lshl_add_u64 v[32:33], s[28:29], 0, v[32:33]
	v_lshl_add_u64 v[34:35], s[28:29], 0, v[34:35]
	v_lshl_add_u64 v[36:37], s[28:29], 0, v[36:37]
	v_lshl_add_u64 v[22:23], v[16:17], 0, v[22:23]
	v_lshl_add_u64 v[24:25], v[16:17], 0, v[24:25]
	v_lshl_add_u64 v[26:27], v[16:17], 0, v[26:27]
	v_lshl_add_u64 v[28:29], v[16:17], 0, v[28:29]
	v_lshl_add_u64 v[30:31], v[16:17], 0, v[30:31]
	v_lshl_add_u64 v[32:33], v[16:17], 0, v[32:33]
	v_lshl_add_u64 v[34:35], v[16:17], 0, v[34:35]
	v_lshl_add_u64 v[36:37], v[16:17], 0, v[36:37]
	global_load_dword v68, v[36:37], off nt
	global_load_dword v69, v[34:35], off nt
	global_load_dword v70, v[32:33], off nt
	global_load_dword v71, v[30:31], off nt
	global_load_dword v72, v[28:29], off nt
	global_load_dword v73, v[26:27], off nt
	global_load_dword v74, v[24:25], off nt
	global_load_dword v75, v[22:23], off nt
	v_lshl_add_u64 v[36:37], v[36:37], 0, s[40:41]
	v_lshl_add_u64 v[34:35], v[34:35], 0, s[40:41]
	v_lshl_add_u64 v[32:33], v[32:33], 0, s[40:41]
	v_lshl_add_u64 v[30:31], v[30:31], 0, s[40:41]
	v_lshl_add_u64 v[28:29], v[28:29], 0, s[40:41]
	v_lshl_add_u64 v[26:27], v[26:27], 0, s[40:41]
	v_lshl_add_u64 v[24:25], v[24:25], 0, s[40:41]
	v_lshl_add_u64 v[22:23], v[22:23], 0, s[40:41]
	global_load_dword v76, v[36:37], off nt
	global_load_dword v77, v[34:35], off nt
	global_load_dword v78, v[32:33], off nt
	global_load_dword v79, v[30:31], off nt
	global_load_dword v80, v[28:29], off nt
	global_load_dword v81, v[26:27], off nt
	global_load_dword v82, v[24:25], off nt
	global_load_dword v83, v[22:23], off nt
	v_lshl_add_u64 v[36:37], v[36:37], 0, s[40:41]
	v_lshl_add_u64 v[34:35], v[34:35], 0, s[40:41]
	v_lshl_add_u64 v[32:33], v[32:33], 0, s[40:41]
	v_lshl_add_u64 v[30:31], v[30:31], 0, s[40:41]
	v_lshl_add_u64 v[28:29], v[28:29], 0, s[40:41]
	v_lshl_add_u64 v[26:27], v[26:27], 0, s[40:41]
	v_lshl_add_u64 v[24:25], v[24:25], 0, s[40:41]
	v_lshl_add_u64 v[22:23], v[22:23], 0, s[40:41]
	global_load_dword v84, v[36:37], off nt
	global_load_dword v85, v[34:35], off nt
	global_load_dword v86, v[32:33], off nt
	global_load_dword v87, v[30:31], off nt
	global_load_dword v88, v[28:29], off nt
	global_load_dword v89, v[26:27], off nt
	global_load_dword v90, v[24:25], off nt
	global_load_dword v91, v[22:23], off nt
	v_lshl_add_u64 v[36:37], v[36:37], 0, s[40:41]
	v_lshl_add_u64 v[34:35], v[34:35], 0, s[40:41]
	v_lshl_add_u64 v[32:33], v[32:33], 0, s[40:41]
	v_lshl_add_u64 v[30:31], v[30:31], 0, s[40:41]
	v_lshl_add_u64 v[28:29], v[28:29], 0, s[40:41]
	v_lshl_add_u64 v[26:27], v[26:27], 0, s[40:41]
	v_lshl_add_u64 v[24:25], v[24:25], 0, s[40:41]
	v_lshl_add_u64 v[22:23], v[22:23], 0, s[40:41]
	global_load_dword v92, v[36:37], off nt
	global_load_dword v93, v[34:35], off nt
	global_load_dword v94, v[32:33], off nt
	global_load_dword v95, v[30:31], off nt
	global_load_dword v96, v[28:29], off nt
	global_load_dword v97, v[26:27], off nt
	global_load_dword v98, v[24:25], off nt
	global_load_dword v99, v[22:23], off nt
	s_waitcnt vmcnt(0)

;     DEV bool next(int i, Unit& u) const { if (!GroupedOrder::next(i, u)) return false; u.A = A; return true; }
;     DEV bool next(int i, Unit& u) const {
;         const long L = (long)i * G + c; if (L >= nwg) return false;
;         int wgid = (int)L; { const int q = nwg / 8, r = nwg % 8, xcd = wgid % 8, off = wgid / 8; wgid = (xcd < r ? xcd * (q + 1) : r * (q + 1) + (xcd - r) * q) + off; }
;         const int nig = 8 * nN, gid = wgid / nig, fm = gid * 8, gsz = (nM - fm) < 8 ? (nM - fm) : 8;
;         u.pm = fm + ((wgid % nig) % gsz); u.pn = (wgid % nig) / gsz; u.e = 0;
;         u.A = A + (size_t)u.pm * BM * K * 2; u.B = Bt + (size_t)u.pn * BM * K * 2; return true;
;     }
; DEV void gemm_g1(const Frame& F0, int l, int vcu) {
;     const Frame F = refresh(F0);
;     const int nin = (l & 1) ? NIN_O : NIN_E;
;     pg8::PlainOrder S; S.init((const void*)(F.ws + WS_XIN), (const bf16_t*)(F.ws + WS_WIN) + (size_t)l * NINMAX * 1024, 1024, MPAD, nin, F.G, vcu);
;     EpiP E; E.O = (bf16_t*)(F.ws + WS_P); E.ldc = nin;
;     pg8::gemm_phase(F.lds, 1024, S, E, F.wave, F.lane);
; }
.LBB0_173:
	s_and_b32 s0, s52, 1
	s_bitcmp1_b32 s52, 0
	v_readlane_b32 s4, v251, 0
	s_cselect_b64 s[56:57], -1, 0
	s_cmp_eq_u32 s0, 0
	v_readlane_b32 s5, v251, 1
	s_cselect_b64 s[58:59], -1, 0
	v_writelane_b32 v253, s0, 49
	s_and_b64 s[4:5], s[58:59], exec
	s_movk_i32 s0, 0x1100
	s_cselect_b32 s26, s0, 0xb00
	s_lshr_b32 s0, s26, 8
	v_readlane_b32 s6, v251, 2
	v_readlane_b32 s7, v251, 3
	s_mulk_i32 s0, 0x44
	v_readlane_b32 s9, v251, 29
	v_mov_b32_e32 v10, v200
	s_mov_b64 s[2:3], s[6:7]
	s_cmp_ge_i32 s95, s0
	s_mov_b32 s53, s1
	s_cbranch_scc1 .LBB0_197
	s_mov_b32 s100, s96
	s_bitcmp1_b32 s52, 0
	s_cbranch_scc1 .Lg1d_norm
	s_cmp_gt_u32 s52, 2
	s_cbranch_scc1 .Lg1d_norm
	v_readlane_b32 s101, v255, 51
	s_cmp_lg_u32 s101, 0x100
	s_cbranch_scc1 .Lg1d_norm
	s_movk_i32 s100, 0xe8
	v_readlane_b32 s101, v255, 48
	s_cmp_ge_u32 s101, 0xe8
	s_cbranch_scc1 .Lsh_entry
.Lg1d_norm:
	v_readlane_b32 s6, v252, 6
	s_lshr_b32 s27, s0, 3
	v_readlane_b32 s7, v252, 7
	s_add_i32 s28, s27, 1
	s_mov_b64 s[4:5], -1
	s_and_b64 vcc, exec, s[6:7]
	s_cbranch_vccz .LBB0_176
	v_readlane_b32 s5, v252, 8
	s_lshl_b32 s4, s28, 2
	s_mul_i32 s5, s27, s5
	s_add_i32 s6, s4, s5
	s_mov_b64 s[4:5], 0

;     DEV bool next(int i, Unit& u) const { if (!GroupedOrder::next(i, u)) return false; u.A = A; return true; }
;     DEV bool next(int i, Unit& u) const {
;         const long L = (long)i * G + c; if (L >= nwg) return false;
;         int wgid = (int)L; { const int q = nwg / 8, r = nwg % 8, xcd = wgid % 8, off = wgid / 8; wgid = (xcd < r ? xcd * (q + 1) : r * (q + 1) + (xcd - r) * q) + off; }
;         const int nig = 8 * nN, gid = wgid / nig, fm = gid * 8, gsz = (nM - fm) < 8 ? (nM - fm) : 8;
;         u.pm = fm + ((wgid % nig) % gsz); u.pn = (wgid % nig) / gsz; u.e = 0;
;         u.A = A + (size_t)u.pm * BM * K * 2; u.B = Bt + (size_t)u.pn * BM * K * 2; return true;
.LBB0_183:
	s_add_i32 s45, s45, 1
	s_mul_i32 s2, s45, s83
	s_mul_hi_u32 s3, s45, s100
	s_add_i32 s3, s3, s2
	s_mul_i32 s2, s45, s100
	s_add_u32 s24, s2, s95
	s_addc_u32 s25, s3, s81
	v_mov_b64_e32 v[2:3], s[0:1]
	v_cmp_ge_i64_e32 vcc, s[24:25], v[2:3]
	v_cmp_lt_i64_e64 s[2:3], s[24:25], v[2:3]
	s_cbranch_vccnz .LBB0_189
	s_ashr_i32 s12, s24, 31
	s_lshr_b32 s12, s12, 29
	s_add_i32 s14, s24, s12
	s_and_b32 s12, s14, -8
	s_sub_i32 s15, s24, s12
	s_cmp_gt_i32 s15, 3
	s_mov_b64 s[12:13], -1
	s_cbranch_scc0 .LBB0_186
	s_add_i32 s12, s15, -4
	s_mul_i32 s12, s12, s27
	s_add_i32 s16, s12, s44
	s_mov_b64 s[12:13], 0

; #define LAS __attribute__((address_space(3)))
; #define NT_LOAD(p) __builtin_nontemporal_load(p)
; DEV void tr_item(const float* W, int ldw, int col0, int k0, bf16_t* WT, int K, int row0, LAS float* scr, int lane) {
; #pragma unroll 8
;     for (int i = 0; i < 32; ++i) { const int kk = 2 * i + (lane >> 5); scr[kk * 33 + (lane & 31)] = NT_LOAD(&W[(size_t)(k0 + kk) * ldw + col0 + (lane & 31)]); }
; DEV void phase_prologue_a(const Frame& F0) {
;     ...
;         constexpr int D_ITEMS = (FF / 64) * 32;
;         for (int it = F.gw; it < NE * D_ITEMS; it += F.NGW) { const int e = it / D_ITEMS, r = it % D_ITEMS, kb = r / 32, nb = r % 32;
;             tr_item(GIN(I_WDOWN) + ((size_t)l * NE + e) * FF * 1024, 1024, 32 * nb, 64 * kb, (bf16_t*)(F.ws + WS_WD) + ((size_t)l * NE + e) * 1024 * FF, FF, 32 * nb, scr, F.lane); }
.Lsh_entry:
	s_bitcmp1_b32 s52, 0
	s_cbranch_scc1 .Lsh_done
	s_cmp_gt_u32 s52, 2
	s_cbranch_scc1 .Lsh_done
	v_readlane_b32 s2, v255, 51
	s_cmp_lg_u32 s2, 0x100
	s_cbranch_scc1 .Lsh_done
	v_readlane_b32 s2, v255, 48
	s_cmp_lt_u32 s2, 0xe8
	s_cbranch_scc1 .Lsh_done
	v_readlane_b32 s3, v251, 29
	s_sub_i32 s2, s2, 0xe8
	s_lshl_b32 s2, s2, 3
	s_add_i32 s2, s2, s3
	v_readlane_b32 s6, v255, 53
	v_readlane_b32 s7, v255, 54
	s_cmp_eq_u32 s52, 2
	s_cbranch_scc1 .Lsh_l2
	v_readlane_b32 s4, v255, 49
	v_readlane_b32 s5, v255, 50
	s_add_u32 s6, s6, 0x22bc8000
	s_addc_u32 s7, s7, 0
	s_lshl_b32 s30, s3, 14
	v_and_b32_e32 v120, 31, v200
	v_lshlrev_b32_e32 v2, 2, v120
	v_lshrrev_b32_e32 v3, 5, v200
	v_and_b32_e32 v4, 7, v200
	v_lshrrev_b32_e32 v6, 3, v200
	v_mul_u32_u24_e32 v7, 33, v3
	v_add_u32_e32 v7, v7, v120
	v_lshl_add_u32 v7, v7, 2, s30
	v_add_u32_e32 v8, 0x400, v7
	v_add_u32_e32 v9, 0x840, v7
	v_add_u32_e32 v10, 0xc40, v7
	v_add_u32_e32 v11, 0x1080, v7
	v_add_u32_e32 v12, 0x1480, v7
	v_add_u32_e32 v13, 0x18c0, v7
	v_add_u32_e32 v14, 0x1cc0, v7
	v_mul_u32_u24_e32 v120, 0x108, v4
	v_add_u32_e32 v120, v120, v6
	v_lshl_add_u32 v15, v120, 2, s30
	v_lshl_add_u32 v122, v3, 12, v2
	v_mov_b32_e32 v123, 0
	v_lshlrev_b32_e32 v124, 4, v4
	v_lshl_add_u32 v124, v6, 12, v124
	v_mov_b32_e32 v125, 0
	s_mov_b64 s[40:41], 0x10000
	s_mov_b64 s[42:43], 0x8000
	s_mov_b64 s[44:45], 0x2000
.Lsh_dn_loop:
	s_lshr_b32 s8, s2, 10
	s_and_b32 s9, s2, 0x3ff
	s_lshr_b32 s10, s9, 5
	s_and_b32 s9, s9, 31
	s_lshl_b32 s24, s10, 18
	s_lshl_b32 s25, s9, 7
	s_add_i32 s24, s24, s25
	s_lshr_b32 s29, s8, 9
	s_lshl_b32 s28, s8, 23
	s_add_u32 s28, s28, s24
	s_addc_u32 s29, s29, 0
	s_add_u32 s28, s28, s4
	s_addc_u32 s29, s29, s5
	s_lshl_b32 s24, s9, 17
	s_lshl_b32 s25, s10, 7
	s_add_i32 s24, s24, s25
	s_lshr_b32 s11, s8, 10
	s_lshl_b32 s10, s8, 22
	s_add_u32 s10, s10, s24
	s_addc_u32 s11, s11, 0
	s_add_u32 s10, s10, s6
	s_addc_u32 s11, s11, s7
	v_lshl_add_u64 v[16:17], s[28:29], 0, v[122:123]
	v_lshl_add_u64 v[18:19], v[16:17], 0, s[44:45]
	v_lshl_add_u64 v[20:21], v[18:19], 0, s[44:45]
	v_lshl_add_u64 v[22:23], v[20:21], 0, s[44:45]
	v_lshl_add_u64 v[24:25], v[22:23], 0, s[44:45]
	v_lshl_add_u64 v[26:27], v[24:25], 0, s[44:45]
	v_lshl_add_u64 v[28:29], v[26:27], 0, s[44:45]
	v_lshl_add_u64 v[30:31], v[28:29], 0, s[44:45]
	global_load_dword v32, v[16:17], off nt
	global_load_dword v33, v[18:19], off nt
	global_load_dword v34, v[20:21], off nt
	global_load_dword v35, v[22:23], off nt
	global_load_dword v36, v[24:25], off nt
	global_load_dword v37, v[26:27], off nt
	global_load_dword v38, v[28:29], off nt
	global_load_dword v39, v[30:31], off nt
	v_lshl_add_u64 v[16:17], v[16:17], 0, s[40:41]
	v_lshl_add_u64 v[18:19], v[18:19], 0, s[40:41]
	v_lshl_add_u64 v[20:21], v[20:21], 0, s[40:41]
	v_lshl_add_u64 v[22:23], v[22:23], 0, s[40:41]
	v_lshl_add_u64 v[24:25], v[24:25], 0, s[40:41]
	v_lshl_add_u64 v[26:27], v[26:27], 0, s[40:41]
	v_lshl_add_u64 v[28:29], v[28:29], 0, s[40:41]
	v_lshl_add_u64 v[30:31], v[30:31], 0, s[40:41]
	global_load_dword v40, v[16:17], off nt
	global_load_dword v41, v[18:19], off nt
	global_load_dword v42, v[20:21], off nt
	global_load_dword v43, v[22:23], off nt
	global_load_dword v44, v[24:25], off nt
	global_load_dword v45, v[26:27], off nt
	global_load_dword v46, v[28:29], off nt
	global_load_dword v47, v[30:31], off nt
	v_lshl_add_u64 v[16:17], v[16:17], 0, s[40:41]
	v_lshl_add_u64 v[18:19], v[18:19], 0, s[40:41]
	v_lshl_add_u64 v[20:21], v[20:21], 0, s[40:41]
	v_lshl_add_u64 v[22:23], v[22:23], 0, s[40:41]
	v_lshl_add_u64 v[24:25], v[24:25], 0, s[40:41]
	v_lshl_add_u64 v[26:27], v[26:27], 0, s[40:41]
	v_lshl_add_u64 v[28:29], v[28:29], 0, s[40:41]
	v_lshl_add_u64 v[30:31], v[30:31], 0, s[40:41]
	global_load_dword v48, v[16:17], off nt
	global_load_dword v49, v[18:19], off nt
	global_load_dword v50, v[20:21], off nt
	global_load_dword v51, v[22:23], off nt
	global_load_dword v52, v[24:25], off nt
	global_load_dword v53, v[26:27], off nt
	global_load_dword v54, v[28:29], off nt
	global_load_dword v55, v[30:31], off nt
	v_lshl_add_u64 v[16:17], v[16:17], 0, s[40:41]
	v_lshl_add_u64 v[18:19], v[18:19], 0, s[40:41]
	v_lshl_add_u64 v[20:21], v[20:21], 0, s[40:41]
	v_lshl_add_u64 v[22:23], v[22:23], 0, s[40:41]
	v_lshl_add_u64 v[24:25], v[24:25], 0, s[40:41]
	v_lshl_add_u64 v[26:27], v[26:27], 0, s[40:41]
	v_lshl_add_u64 v[28:29], v[28:29], 0, s[40:41]
	v_lshl_add_u64 v[30:31], v[30:31], 0, s[40:41]
	global_load_dword v56, v[16:17], off nt
	global_load_dword v57, v[18:19], off nt
	global_load_dword v58, v[20:21], off nt
	global_load_dword v59, v[22:23], off nt
	global_load_dword v60, v[24:25], off nt
	global_load_dword v61, v[26:27], off nt
	global_load_dword v62, v[28:29], off nt
	global_load_dword v63, v[30:31], off nt
	v_lshl_add_u64 v[64:65], s[10:11], 0, v[124:125]
	v_lshl_add_u64 v[66:67], v[64:65], 0, s[42:43]
	v_lshl_add_u64 v[68:69], v[66:67], 0, s[42:43]
	v_lshl_add_u64 v[70:71], v[68:69], 0, s[42:43]
	s_add_i32 s31, s2, 0xc0
	s_lshr_b32 s8, s31, 10
	s_and_b32 s9, s31, 0x3ff
	s_lshr_b32 s10, s9, 5
	s_and_b32 s9, s9, 31
	s_lshl_b32 s24, s10, 18
	s_lshl_b32 s25, s9, 7
	s_add_i32 s24, s24, s25
	s_lshr_b32 s29, s8, 9
	s_lshl_b32 s28, s8, 23
	s_add_u32 s28, s28, s24
	s_addc_u32 s29, s29, 0
	s_add_u32 s28, s28, s4
	s_addc_u32 s29, s29, s5
	s_lshl_b32 s24, s9, 17
	s_lshl_b32 s25, s10, 7
	s_add_i32 s24, s24, s25
	s_lshr_b32 s11, s8, 10
	s_lshl_b32 s10, s8, 22
	s_add_u32 s10, s10, s24
	s_addc_u32 s11, s11, 0
	s_add_u32 s10, s10, s6
	s_addc_u32 s11, s11, s7
	v_lshl_add_u64 v[16:17], s[28:29], 0, v[122:123]
	v_lshl_add_u64 v[18:19], v[16:17], 0, s[44:45]
; #define WAVE_LDS_SYNC() do { int _z = 0; (void)emu::wave_xchg(&_z, 4); } while (0)
; #define LAS __attribute__((address_space(3)))
; #define WAVE_LDS_SYNC() asm volatile("s_waitcnt lgkmcnt(0)" ::: "memory")
; #define NT_LOAD(p) __builtin_nontemporal_load(p)
; #define NT_STORE(v, p) __builtin_nontemporal_store((v), (p))
; DEV unsigned pk2(float lo, float hi) { return f2bf(lo) | (f2bf(hi) << 16); }
; DEV unsigned pk2(float lo, float hi) { const f32x2n_t v = {lo, hi}; return __builtin_bit_cast(unsigned, __builtin_convertvector(v, bf16x2n_t)); }
; DEV void tr_item(const float* W, int ldw, int col0, int k0, bf16_t* WT, int K, int row0, LAS float* scr, int lane) {
; #pragma unroll 8
;     for (int i = 0; i < 32; ++i) { const int kk = 2 * i + (lane >> 5); scr[kk * 33 + (lane & 31)] = NT_LOAD(&W[(size_t)(k0 + kk) * ldw + col0 + (lane & 31)]); }
;     WAVE_LDS_SYNC();
;     const int c = lane & 7;
; #pragma unroll
;     for (int j = 0; j < 4; ++j) { const int n = (lane >> 3) + 8 * j; const LAS float* s = scr + (8 * c) * 33 + n;
;         u32x4 o; o.x = pk2(s[0 * 33], s[1 * 33]); o.y = pk2(s[2 * 33], s[3 * 33]); o.z = pk2(s[4 * 33], s[5 * 33]); o.w = pk2(s[6 * 33], s[7 * 33]);
;         NT_STORE(o, (u32x4*)(WT + (size_t)(row0 + n) * K + k0 + 8 * c)); }
	v_lshl_add_u64 v[20:21], v[18:19], 0, s[44:45]
	v_lshl_add_u64 v[22:23], v[20:21], 0, s[44:45]
	v_lshl_add_u64 v[24:25], v[22:23], 0, s[44:45]
	v_lshl_add_u64 v[26:27], v[24:25], 0, s[44:45]
	v_lshl_add_u64 v[28:29], v[26:27], 0, s[44:45]
	v_lshl_add_u64 v[30:31], v[28:29], 0, s[44:45]
	global_load_dword v162, v[16:17], off nt
	global_load_dword v163, v[18:19], off nt
	global_load_dword v164, v[20:21], off nt
	global_load_dword v165, v[22:23], off nt
	global_load_dword v166, v[24:25], off nt
	global_load_dword v167, v[26:27], off nt
	global_load_dword v168, v[28:29], off nt
	global_load_dword v169, v[30:31], off nt
	v_lshl_add_u64 v[16:17], v[16:17], 0, s[40:41]
	v_lshl_add_u64 v[18:19], v[18:19], 0, s[40:41]
	v_lshl_add_u64 v[20:21], v[20:21], 0, s[40:41]
	v_lshl_add_u64 v[22:23], v[22:23], 0, s[40:41]
	v_lshl_add_u64 v[24:25], v[24:25], 0, s[40:41]
	v_lshl_add_u64 v[26:27], v[26:27], 0, s[40:41]
	v_lshl_add_u64 v[28:29], v[28:29], 0, s[40:41]
	v_lshl_add_u64 v[30:31], v[30:31], 0, s[40:41]
	global_load_dword v170, v[16:17], off nt
	global_load_dword v171, v[18:19], off nt
	global_load_dword v172, v[20:21], off nt
	global_load_dword v173, v[22:23], off nt
	global_load_dword v174, v[24:25], off nt
	global_load_dword v175, v[26:27], off nt
	global_load_dword v176, v[28:29], off nt
	global_load_dword v177, v[30:31], off nt
	v_lshl_add_u64 v[16:17], v[16:17], 0, s[40:41]
	v_lshl_add_u64 v[18:19], v[18:19], 0, s[40:41]
	v_lshl_add_u64 v[20:21], v[20:21], 0, s[40:41]
	v_lshl_add_u64 v[22:23], v[22:23], 0, s[40:41]
	v_lshl_add_u64 v[24:25], v[24:25], 0, s[40:41]
	v_lshl_add_u64 v[26:27], v[26:27], 0, s[40:41]
	v_lshl_add_u64 v[28:29], v[28:29], 0, s[40:41]
	v_lshl_add_u64 v[30:31], v[30:31], 0, s[40:41]
	global_load_dword v178, v[16:17], off nt
	global_load_dword v179, v[18:19], off nt
	global_load_dword v180, v[20:21], off nt
	global_load_dword v181, v[22:23], off nt
	global_load_dword v182, v[24:25], off nt
	global_load_dword v183, v[26:27], off nt
	global_load_dword v184, v[28:29], off nt
	global_load_dword v185, v[30:31], off nt
	v_lshl_add_u64 v[16:17], v[16:17], 0, s[40:41]
	v_lshl_add_u64 v[18:19], v[18:19], 0, s[40:41]
	v_lshl_add_u64 v[20:21], v[20:21], 0, s[40:41]
	v_lshl_add_u64 v[22:23], v[22:23], 0, s[40:41]
	v_lshl_add_u64 v[24:25], v[24:25], 0, s[40:41]
	v_lshl_add_u64 v[26:27], v[26:27], 0, s[40:41]
	v_lshl_add_u64 v[28:29], v[28:29], 0, s[40:41]
	v_lshl_add_u64 v[30:31], v[30:31], 0, s[40:41]
	global_load_dword v186, v[16:17], off nt
	global_load_dword v187, v[18:19], off nt
	global_load_dword v188, v[20:21], off nt
	global_load_dword v189, v[22:23], off nt
	global_load_dword v190, v[24:25], off nt
	global_load_dword v191, v[26:27], off nt
	global_load_dword v192, v[28:29], off nt
	global_load_dword v193, v[30:31], off nt
	v_lshl_add_u64 v[126:127], s[10:11], 0, v[124:125]
	v_lshl_add_u64 v[128:129], v[126:127], 0, s[42:43]
	v_lshl_add_u64 v[130:131], v[128:129], 0, s[42:43]
	v_lshl_add_u64 v[132:133], v[130:131], 0, s[42:43]
	s_waitcnt vmcnt(62)
	ds_write2_b32 v7, v32, v33 offset1:66
	s_waitcnt vmcnt(60)
	ds_write2_b32 v7, v34, v35 offset0:132 offset1:198
	s_waitcnt vmcnt(58)
	ds_write2_b32 v8, v36, v37 offset0:8 offset1:74
	s_waitcnt vmcnt(56)
	ds_write2_b32 v8, v38, v39 offset0:140 offset1:206
	s_waitcnt vmcnt(54)
	ds_write2_b32 v9, v40, v41 offset1:66
	s_waitcnt vmcnt(52)
	ds_write2_b32 v9, v42, v43 offset0:132 offset1:198
	s_waitcnt vmcnt(50)
	ds_write2_b32 v10, v44, v45 offset0:8 offset1:74
	s_waitcnt vmcnt(48)
	ds_write2_b32 v10, v46, v47 offset0:140 offset1:206
	s_waitcnt vmcnt(46)
	ds_write2_b32 v11, v48, v49 offset1:66
	s_waitcnt vmcnt(44)
	ds_write2_b32 v11, v50, v51 offset0:132 offset1:198
	s_waitcnt vmcnt(42)
	ds_write2_b32 v12, v52, v53 offset0:8 offset1:74
	s_waitcnt vmcnt(40)
	ds_write2_b32 v12, v54, v55 offset0:140 offset1:206
	s_waitcnt vmcnt(38)
	ds_write2_b32 v13, v56, v57 offset1:66
	s_waitcnt vmcnt(36)
	ds_write2_b32 v13, v58, v59 offset0:132 offset1:198
	s_waitcnt vmcnt(34)
	ds_write2_b32 v14, v60, v61 offset0:8 offset1:74
	s_waitcnt vmcnt(32)
	ds_write2_b32 v14, v62, v63 offset0:140 offset1:206
	ds_read2_b32 v[72:73], v15 offset1:8
	ds_read2_b32 v[74:75], v15 offset0:33 offset1:41
	ds_read2_b32 v[76:77], v15 offset0:66 offset1:74
	ds_read2_b32 v[78:79], v15 offset0:99 offset1:107
	ds_read2_b32 v[80:81], v15 offset0:132 offset1:140
	ds_read2_b32 v[82:83], v15 offset0:165 offset1:173
	ds_read2_b32 v[84:85], v15 offset0:198 offset1:206
	ds_read2_b32 v[86:87], v15 offset0:231 offset1:239
	ds_read2_b32 v[88:89], v15 offset0:16 offset1:24
	ds_read2_b32 v[90:91], v15 offset0:49 offset1:57
	ds_read2_b32 v[92:93], v15 offset0:82 offset1:90
	ds_read2_b32 v[94:95], v15 offset0:115 offset1:123
	s_waitcnt lgkmcnt(4)
	v_cvt_pk_bf16_f32 v104, v72, v74
	v_cvt_pk_bf16_f32 v105, v76, v78
	v_cvt_pk_bf16_f32 v106, v80, v82
	v_cvt_pk_bf16_f32 v107, v84, v86
	v_cvt_pk_bf16_f32 v108, v73, v75
	v_cvt_pk_bf16_f32 v109, v77, v79
	v_cvt_pk_bf16_f32 v110, v81, v83
	v_cvt_pk_bf16_f32 v111, v85, v87
	ds_read2_b32 v[96:97], v15 offset0:148 offset1:156
	ds_read2_b32 v[98:99], v15 offset0:181 offset1:189
	ds_read2_b32 v[100:101], v15 offset0:214 offset1:222
	ds_read2_b32 v[102:103], v15 offset0:247 offset1:255
	global_store_dwordx4 v[64:65], v[104:107], off nt
	global_store_dwordx4 v[66:67], v[108:111], off nt
	s_waitcnt lgkmcnt(0)
	v_cvt_pk_bf16_f32 v112, v88, v90
	v_cvt_pk_bf16_f32 v113, v92, v94
	v_cvt_pk_bf16_f32 v114, v96, v98
	v_cvt_pk_bf16_f32 v115, v100, v102
	v_cvt_pk_bf16_f32 v116, v89, v91
	v_cvt_pk_bf16_f32 v117, v93, v95
	v_cvt_pk_bf16_f32 v118, v97, v99
	v_cvt_pk_bf16_f32 v119, v101, v103
	global_store_dwordx4 v[68:69], v[112:115], off nt
	global_store_dwordx4 v[70:71], v[116:119], off nt
	s_waitcnt vmcnt(34)
; #define WAVE_LDS_SYNC() do { int _z = 0; (void)emu::wave_xchg(&_z, 4); } while (0)
; #define LAS __attribute__((address_space(3)))
; #define WAVE_LDS_SYNC() asm volatile("s_waitcnt lgkmcnt(0)" ::: "memory")
; #define NT_LOAD(p) __builtin_nontemporal_load(p)
; #define NT_STORE(v, p) __builtin_nontemporal_store((v), (p))
; DEV unsigned pk2(float lo, float hi) { return f2bf(lo) | (f2bf(hi) << 16); }
; DEV unsigned pk2(float lo, float hi) { const f32x2n_t v = {lo, hi}; return __builtin_bit_cast(unsigned, __builtin_convertvector(v, bf16x2n_t)); }
; DEV void tr_item(const float* W, int ldw, int col0, int k0, bf16_t* WT, int K, int row0, LAS float* scr, int lane) {
; #pragma unroll 8
;     for (int i = 0; i < 32; ++i) { const int kk = 2 * i + (lane >> 5); scr[kk * 33 + (lane & 31)] = NT_LOAD(&W[(size_t)(k0 + kk) * ldw + col0 + (lane & 31)]); }
;     WAVE_LDS_SYNC();
;     const int c = lane & 7;
; #pragma unroll
;     for (int j = 0; j < 4; ++j) { const int n = (lane >> 3) + 8 * j; const LAS float* s = scr + (8 * c) * 33 + n;
;         u32x4 o; o.x = pk2(s[0 * 33], s[1 * 33]); o.y = pk2(s[2 * 33], s[3 * 33]); o.z = pk2(s[4 * 33], s[5 * 33]); o.w = pk2(s[6 * 33], s[7 * 33]);
;         NT_STORE(o, (u32x4*)(WT + (size_t)(row0 + n) * K + k0 + 8 * c)); }
; DEV void phase_prologue_a(const Frame& F0) {
;     ...
;         constexpr int GU_NB = 2 * FF / 32, GU_ITEMS = 16 * GU_NB;
;         for (int it = F.gw; it < NE * GU_ITEMS; it += F.NGW) { const int e = it / GU_ITEMS, r = it % GU_ITEMS, kb = r / GU_NB, nb = r % GU_NB; const int d0 = 32 * nb, j = d0 >> 8, w = d0 & 255;
;             const float* src = (w < 128 ? GIN(I_WGATE) : GIN(I_WUP)) + ((size_t)l * NE + e) * 1024 * FF;
;             tr_item(src, FF, 128 * j + (w & 127), 64 * kb, (bf16_t*)(F.ws + WS_WGU) + ((size_t)l * NE + e) * 2 * FF * 1024, 1024, d0, scr, F.lane); }
	ds_write2_b32 v7, v162, v163 offset1:66
	s_waitcnt vmcnt(32)
	ds_write2_b32 v7, v164, v165 offset0:132 offset1:198
	s_waitcnt vmcnt(30)
	ds_write2_b32 v8, v166, v167 offset0:8 offset1:74
	s_waitcnt vmcnt(28)
	ds_write2_b32 v8, v168, v169 offset0:140 offset1:206
	s_waitcnt vmcnt(26)
	ds_write2_b32 v9, v170, v171 offset1:66
	s_waitcnt vmcnt(24)
	ds_write2_b32 v9, v172, v173 offset0:132 offset1:198
	s_waitcnt vmcnt(22)
	ds_write2_b32 v10, v174, v175 offset0:8 offset1:74
	s_waitcnt vmcnt(20)
	ds_write2_b32 v10, v176, v177 offset0:140 offset1:206
	s_waitcnt vmcnt(18)
	ds_write2_b32 v11, v178, v179 offset1:66
	s_waitcnt vmcnt(16)
	ds_write2_b32 v11, v180, v181 offset0:132 offset1:198
	s_waitcnt vmcnt(14)
	ds_write2_b32 v12, v182, v183 offset0:8 offset1:74
	s_waitcnt vmcnt(12)
	ds_write2_b32 v12, v184, v185 offset0:140 offset1:206
	s_waitcnt vmcnt(10)
	ds_write2_b32 v13, v186, v187 offset1:66
	s_waitcnt vmcnt(8)
	ds_write2_b32 v13, v188, v189 offset0:132 offset1:198
	s_waitcnt vmcnt(6)
	ds_write2_b32 v14, v190, v191 offset0:8 offset1:74
	s_waitcnt vmcnt(4)
	ds_write2_b32 v14, v192, v193 offset0:140 offset1:206
	ds_read2_b32 v[72:73], v15 offset1:8
	ds_read2_b32 v[74:75], v15 offset0:33 offset1:41
	ds_read2_b32 v[76:77], v15 offset0:66 offset1:74
	ds_read2_b32 v[78:79], v15 offset0:99 offset1:107
	ds_read2_b32 v[80:81], v15 offset0:132 offset1:140
	ds_read2_b32 v[82:83], v15 offset0:165 offset1:173
	ds_read2_b32 v[84:85], v15 offset0:198 offset1:206
	ds_read2_b32 v[86:87], v15 offset0:231 offset1:239
	ds_read2_b32 v[88:89], v15 offset0:16 offset1:24
	ds_read2_b32 v[90:91], v15 offset0:49 offset1:57
	ds_read2_b32 v[92:93], v15 offset0:82 offset1:90
	ds_read2_b32 v[94:95], v15 offset0:115 offset1:123
	s_waitcnt lgkmcnt(4)
	v_cvt_pk_bf16_f32 v104, v72, v74
	v_cvt_pk_bf16_f32 v105, v76, v78
	v_cvt_pk_bf16_f32 v106, v80, v82
	v_cvt_pk_bf16_f32 v107, v84, v86
	v_cvt_pk_bf16_f32 v108, v73, v75
	v_cvt_pk_bf16_f32 v109, v77, v79
	v_cvt_pk_bf16_f32 v110, v81, v83
	v_cvt_pk_bf16_f32 v111, v85, v87
	ds_read2_b32 v[96:97], v15 offset0:148 offset1:156
	ds_read2_b32 v[98:99], v15 offset0:181 offset1:189
	ds_read2_b32 v[100:101], v15 offset0:214 offset1:222
	ds_read2_b32 v[102:103], v15 offset0:247 offset1:255
	global_store_dwordx4 v[126:127], v[104:107], off nt
	global_store_dwordx4 v[128:129], v[108:111], off nt
	s_waitcnt lgkmcnt(0)
	v_cvt_pk_bf16_f32 v112, v88, v90
	v_cvt_pk_bf16_f32 v113, v92, v94
	v_cvt_pk_bf16_f32 v114, v96, v98
	v_cvt_pk_bf16_f32 v115, v100, v102
	v_cvt_pk_bf16_f32 v116, v89, v91
	v_cvt_pk_bf16_f32 v117, v93, v95
	v_cvt_pk_bf16_f32 v118, v97, v99
	v_cvt_pk_bf16_f32 v119, v101, v103
	global_store_dwordx4 v[130:131], v[112:115], off nt
	global_store_dwordx4 v[132:133], v[116:119], off nt
	s_add_i32 s2, s2, 0x180
	s_cmp_lt_u32 s2, 0x1e00
	s_cbranch_scc1 .Lsh_dn_loop
	s_branch .Lsh_done
.Lsh_l2:
	v_readlane_b32 s4, v255, 55
	v_readlane_b32 s5, v255, 56
	v_readlane_b32 s34, v255, 57
	v_readlane_b32 s35, v255, 58
	s_add_u32 s6, s6, 0x2bc8000
	s_addc_u32 s7, s7, 0
	s_mov_b32 s8, 0x18000000
	s_add_u32 s4, s4, s8
	s_addc_u32 s5, s5, 0
	s_add_u32 s34, s34, s8
	s_addc_u32 s35, s35, 0
	s_add_u32 s6, s6, s8
	s_addc_u32 s7, s7, 0
	s_add_i32 s2, s2, 0x6500
	s_lshl_b32 s30, s3, 14
	v_and_b32_e32 v120, 31, v200
	v_lshlrev_b32_e32 v2, 2, v120
	v_lshrrev_b32_e32 v3, 5, v200
	v_and_b32_e32 v4, 7, v200
	v_lshrrev_b32_e32 v6, 3, v200
	v_mul_u32_u24_e32 v7, 33, v3
	v_add_u32_e32 v7, v7, v120
	v_lshl_add_u32 v7, v7, 2, s30
	v_add_u32_e32 v8, 0x400, v7
	v_add_u32_e32 v9, 0x840, v7
	v_add_u32_e32 v10, 0xc40, v7
	v_add_u32_e32 v11, 0x1080, v7
	v_add_u32_e32 v12, 0x1480, v7
	v_add_u32_e32 v13, 0x18c0, v7
	v_add_u32_e32 v14, 0x1cc0, v7
	v_mul_u32_u24_e32 v120, 0x108, v4
	v_add_u32_e32 v120, v120, v6
	v_lshl_add_u32 v15, v120, 2, s30
	v_lshl_add_u32 v122, v3, 13, v2
	v_mov_b32_e32 v123, 0
	v_lshlrev_b32_e32 v124, 4, v4
	v_lshl_add_u32 v124, v6, 11, v124
	v_mov_b32_e32 v125, 0
	s_mov_b64 s[40:41], 0x20000
	s_mov_b64 s[42:43], 0x4000
	s_mov_b64 s[44:45], 0x4000
.Lsh_gu_loop:
	s_lshr_b32 s8, s2, 11
	s_and_b32 s9, s2, 0x7ff
	s_lshr_b32 s10, s9, 7
	s_and_b32 s9, s9, 0x7f
	s_lshl_b32 s24, s10, 19
	s_lshr_b32 s25, s9, 3
	s_lshl_b32 s25, s25, 9
	s_add_i32 s24, s24, s25
	s_and_b32 s25, s9, 3
	s_lshl_b32 s25, s25, 7
	s_add_i32 s24, s24, s25
	s_lshr_b32 s29, s8, 9
	s_lshl_b32 s28, s8, 23
	s_add_u32 s28, s28, s24
	s_addc_u32 s29, s29, 0
	s_bitcmp0_b32 s9, 2
	s_cselect_b32 s24, s4, s34
	s_cselect_b32 s25, s5, s35
	s_add_u32 s28, s28, s24
	s_addc_u32 s29, s29, s25
	s_lshl_b32 s24, s9, 16
	s_lshl_b32 s25, s10, 7
	s_add_i32 s24, s24, s25
	s_lshr_b32 s11, s8, 9
	s_lshl_b32 s10, s8, 23
	s_add_u32 s10, s10, s24
	s_addc_u32 s11, s11, 0
	s_add_u32 s10, s10, s6
	s_addc_u32 s11, s11, s7
	v_lshl_add_u64 v[16:17], s[28:29], 0, v[122:123]
	v_lshl_add_u64 v[18:19], v[16:17], 0, s[44:45]
	v_lshl_add_u64 v[20:21], v[18:19], 0, s[44:45]
	v_lshl_add_u64 v[22:23], v[20:21], 0, s[44:45]
	v_lshl_add_u64 v[24:25], v[22:23], 0, s[44:45]
	v_lshl_add_u64 v[26:27], v[24:25], 0, s[44:45]
	v_lshl_add_u64 v[28:29], v[26:27], 0, s[44:45]
	v_lshl_add_u64 v[30:31], v[28:29], 0, s[44:45]
	global_load_dword v32, v[16:17], off nt
	global_load_dword v33, v[18:19], off nt
	global_load_dword v34, v[20:21], off nt
	global_load_dword v35, v[22:23], off nt
	global_load_dword v36, v[24:25], off nt
	global_load_dword v37, v[26:27], off nt
	global_load_dword v38, v[28:29], off nt
	global_load_dword v39, v[30:31], off nt
	v_lshl_add_u64 v[16:17], v[16:17], 0, s[40:41]
	v_lshl_add_u64 v[18:19], v[18:19], 0, s[40:41]
	v_lshl_add_u64 v[20:21], v[20:21], 0, s[40:41]
	v_lshl_add_u64 v[22:23], v[22:23], 0, s[40:41]
; #define LAS __attribute__((address_space(3)))
; #define NT_LOAD(p) __builtin_nontemporal_load(p)
; DEV void tr_item(const float* W, int ldw, int col0, int k0, bf16_t* WT, int K, int row0, LAS float* scr, int lane) {
; #pragma unroll 8
;     for (int i = 0; i < 32; ++i) { const int kk = 2 * i + (lane >> 5); scr[kk * 33 + (lane & 31)] = NT_LOAD(&W[(size_t)(k0 + kk) * ldw + col0 + (lane & 31)]); }
; DEV void phase_prologue_a(const Frame& F0) {
;     ...
;         constexpr int GU_NB = 2 * FF / 32, GU_ITEMS = 16 * GU_NB;
;         for (int it = F.gw; it < NE * GU_ITEMS; it += F.NGW) { const int e = it / GU_ITEMS, r = it % GU_ITEMS, kb = r / GU_NB, nb = r % GU_NB; const int d0 = 32 * nb, j = d0 >> 8, w = d0 & 255;
;             const float* src = (w < 128 ? GIN(I_WGATE) : GIN(I_WUP)) + ((size_t)l * NE + e) * 1024 * FF;
;             tr_item(src, FF, 128 * j + (w & 127), 64 * kb, (bf16_t*)(F.ws + WS_WGU) + ((size_t)l * NE + e) * 2 * FF * 1024, 1024, d0, scr, F.lane); }
	v_lshl_add_u64 v[24:25], v[24:25], 0, s[40:41]
	v_lshl_add_u64 v[26:27], v[26:27], 0, s[40:41]
	v_lshl_add_u64 v[28:29], v[28:29], 0, s[40:41]
	v_lshl_add_u64 v[30:31], v[30:31], 0, s[40:41]
	global_load_dword v40, v[16:17], off nt
	global_load_dword v41, v[18:19], off nt
	global_load_dword v42, v[20:21], off nt
	global_load_dword v43, v[22:23], off nt
	global_load_dword v44, v[24:25], off nt
	global_load_dword v45, v[26:27], off nt
	global_load_dword v46, v[28:29], off nt
	global_load_dword v47, v[30:31], off nt
	v_lshl_add_u64 v[16:17], v[16:17], 0, s[40:41]
	v_lshl_add_u64 v[18:19], v[18:19], 0, s[40:41]
	v_lshl_add_u64 v[20:21], v[20:21], 0, s[40:41]
	v_lshl_add_u64 v[22:23], v[22:23], 0, s[40:41]
	v_lshl_add_u64 v[24:25], v[24:25], 0, s[40:41]
	v_lshl_add_u64 v[26:27], v[26:27], 0, s[40:41]
	v_lshl_add_u64 v[28:29], v[28:29], 0, s[40:41]
	v_lshl_add_u64 v[30:31], v[30:31], 0, s[40:41]
	global_load_dword v48, v[16:17], off nt
	global_load_dword v49, v[18:19], off nt
	global_load_dword v50, v[20:21], off nt
	global_load_dword v51, v[22:23], off nt
	global_load_dword v52, v[24:25], off nt
	global_load_dword v53, v[26:27], off nt
	global_load_dword v54, v[28:29], off nt
	global_load_dword v55, v[30:31], off nt
	v_lshl_add_u64 v[16:17], v[16:17], 0, s[40:41]
	v_lshl_add_u64 v[18:19], v[18:19], 0, s[40:41]
	v_lshl_add_u64 v[20:21], v[20:21], 0, s[40:41]
	v_lshl_add_u64 v[22:23], v[22:23], 0, s[40:41]
	v_lshl_add_u64 v[24:25], v[24:25], 0, s[40:41]
	v_lshl_add_u64 v[26:27], v[26:27], 0, s[40:41]
	v_lshl_add_u64 v[28:29], v[28:29], 0, s[40:41]
	v_lshl_add_u64 v[30:31], v[30:31], 0, s[40:41]
	global_load_dword v56, v[16:17], off nt
	global_load_dword v57, v[18:19], off nt
	global_load_dword v58, v[20:21], off nt
	global_load_dword v59, v[22:23], off nt
	global_load_dword v60, v[24:25], off nt
	global_load_dword v61, v[26:27], off nt
	global_load_dword v62, v[28:29], off nt
	global_load_dword v63, v[30:31], off nt
	v_lshl_add_u64 v[64:65], s[10:11], 0, v[124:125]
	v_lshl_add_u64 v[66:67], v[64:65], 0, s[42:43]
	v_lshl_add_u64 v[68:69], v[66:67], 0, s[42:43]
	v_lshl_add_u64 v[70:71], v[68:69], 0, s[42:43]
	s_add_i32 s31, s2, 0xc0
	s_lshr_b32 s8, s31, 11
	s_and_b32 s9, s31, 0x7ff
	s_lshr_b32 s10, s9, 7
	s_and_b32 s9, s9, 0x7f
	s_lshl_b32 s24, s10, 19
	s_lshr_b32 s25, s9, 3
	s_lshl_b32 s25, s25, 9
	s_add_i32 s24, s24, s25
	s_and_b32 s25, s9, 3
	s_lshl_b32 s25, s25, 7
	s_add_i32 s24, s24, s25
	s_lshr_b32 s29, s8, 9
	s_lshl_b32 s28, s8, 23
	s_add_u32 s28, s28, s24
	s_addc_u32 s29, s29, 0
	s_bitcmp0_b32 s9, 2
	s_cselect_b32 s24, s4, s34
	s_cselect_b32 s25, s5, s35
	s_add_u32 s28, s28, s24
	s_addc_u32 s29, s29, s25
	s_lshl_b32 s24, s9, 16
	s_lshl_b32 s25, s10, 7
	s_add_i32 s24, s24, s25
	s_lshr_b32 s11, s8, 9
	s_lshl_b32 s10, s8, 23
	s_add_u32 s10, s10, s24
	s_addc_u32 s11, s11, 0
	s_add_u32 s10, s10, s6
	s_addc_u32 s11, s11, s7
	v_lshl_add_u64 v[16:17], s[28:29], 0, v[122:123]
	v_lshl_add_u64 v[18:19], v[16:17], 0, s[44:45]
	v_lshl_add_u64 v[20:21], v[18:19], 0, s[44:45]
	v_lshl_add_u64 v[22:23], v[20:21], 0, s[44:45]
	v_lshl_add_u64 v[24:25], v[22:23], 0, s[44:45]
	v_lshl_add_u64 v[26:27], v[24:25], 0, s[44:45]
	v_lshl_add_u64 v[28:29], v[26:27], 0, s[44:45]
	v_lshl_add_u64 v[30:31], v[28:29], 0, s[44:45]
	global_load_dword v162, v[16:17], off nt
	global_load_dword v163, v[18:19], off nt
	global_load_dword v164, v[20:21], off nt
	global_load_dword v165, v[22:23], off nt
	global_load_dword v166, v[24:25], off nt
	global_load_dword v167, v[26:27], off nt
	global_load_dword v168, v[28:29], off nt
	global_load_dword v169, v[30:31], off nt
	v_lshl_add_u64 v[16:17], v[16:17], 0, s[40:41]
	v_lshl_add_u64 v[18:19], v[18:19], 0, s[40:41]
	v_lshl_add_u64 v[20:21], v[20:21], 0, s[40:41]
	v_lshl_add_u64 v[22:23], v[22:23], 0, s[40:41]
	v_lshl_add_u64 v[24:25], v[24:25], 0, s[40:41]
	v_lshl_add_u64 v[26:27], v[26:27], 0, s[40:41]
	v_lshl_add_u64 v[28:29], v[28:29], 0, s[40:41]
	v_lshl_add_u64 v[30:31], v[30:31], 0, s[40:41]
	global_load_dword v170, v[16:17], off nt
	global_load_dword v171, v[18:19], off nt
	global_load_dword v172, v[20:21], off nt
	global_load_dword v173, v[22:23], off nt
	global_load_dword v174, v[24:25], off nt
	global_load_dword v175, v[26:27], off nt
	global_load_dword v176, v[28:29], off nt
	global_load_dword v177, v[30:31], off nt
	v_lshl_add_u64 v[16:17], v[16:17], 0, s[40:41]
	v_lshl_add_u64 v[18:19], v[18:19], 0, s[40:41]
	v_lshl_add_u64 v[20:21], v[20:21], 0, s[40:41]
	v_lshl_add_u64 v[22:23], v[22:23], 0, s[40:41]
	v_lshl_add_u64 v[24:25], v[24:25], 0, s[40:41]
	v_lshl_add_u64 v[26:27], v[26:27], 0, s[40:41]
	v_lshl_add_u64 v[28:29], v[28:29], 0, s[40:41]
	v_lshl_add_u64 v[30:31], v[30:31], 0, s[40:41]
	global_load_dword v178, v[16:17], off nt
	global_load_dword v179, v[18:19], off nt
	global_load_dword v180, v[20:21], off nt
	global_load_dword v181, v[22:23], off nt
	global_load_dword v182, v[24:25], off nt
	global_load_dword v183, v[26:27], off nt
	global_load_dword v184, v[28:29], off nt
	global_load_dword v185, v[30:31], off nt
	v_lshl_add_u64 v[16:17], v[16:17], 0, s[40:41]
	v_lshl_add_u64 v[18:19], v[18:19], 0, s[40:41]
	v_lshl_add_u64 v[20:21], v[20:21], 0, s[40:41]
	v_lshl_add_u64 v[22:23], v[22:23], 0, s[40:41]
	v_lshl_add_u64 v[24:25], v[24:25], 0, s[40:41]
	v_lshl_add_u64 v[26:27], v[26:27], 0, s[40:41]
	v_lshl_add_u64 v[28:29], v[28:29], 0, s[40:41]
	v_lshl_add_u64 v[30:31], v[30:31], 0, s[40:41]
	global_load_dword v186, v[16:17], off nt
	global_load_dword v187, v[18:19], off nt
	global_load_dword v188, v[20:21], off nt
	global_load_dword v189, v[22:23], off nt
	global_load_dword v190, v[24:25], off nt
	global_load_dword v191, v[26:27], off nt
	global_load_dword v192, v[28:29], off nt
	global_load_dword v193, v[30:31], off nt
	v_lshl_add_u64 v[126:127], s[10:11], 0, v[124:125]
	v_lshl_add_u64 v[128:129], v[126:127], 0, s[42:43]
	v_lshl_add_u64 v[130:131], v[128:129], 0, s[42:43]
	v_lshl_add_u64 v[132:133], v[130:131], 0, s[42:43]
	s_waitcnt vmcnt(62)
; #define WAVE_LDS_SYNC() do { int _z = 0; (void)emu::wave_xchg(&_z, 4); } while (0)
; #define LAS __attribute__((address_space(3)))
; #define WAVE_LDS_SYNC() asm volatile("s_waitcnt lgkmcnt(0)" ::: "memory")
; #define NT_LOAD(p) __builtin_nontemporal_load(p)
; #define NT_STORE(v, p) __builtin_nontemporal_store((v), (p))
; DEV unsigned pk2(float lo, float hi) { return f2bf(lo) | (f2bf(hi) << 16); }
; DEV unsigned pk2(float lo, float hi) { const f32x2n_t v = {lo, hi}; return __builtin_bit_cast(unsigned, __builtin_convertvector(v, bf16x2n_t)); }
; DEV void tr_item(const float* W, int ldw, int col0, int k0, bf16_t* WT, int K, int row0, LAS float* scr, int lane) {
; #pragma unroll 8
;     for (int i = 0; i < 32; ++i) { const int kk = 2 * i + (lane >> 5); scr[kk * 33 + (lane & 31)] = NT_LOAD(&W[(size_t)(k0 + kk) * ldw + col0 + (lane & 31)]); }
;     WAVE_LDS_SYNC();
;     const int c = lane & 7;
; #pragma unroll
;     for (int j = 0; j < 4; ++j) { const int n = (lane >> 3) + 8 * j; const LAS float* s = scr + (8 * c) * 33 + n;
;         u32x4 o; o.x = pk2(s[0 * 33], s[1 * 33]); o.y = pk2(s[2 * 33], s[3 * 33]); o.z = pk2(s[4 * 33], s[5 * 33]); o.w = pk2(s[6 * 33], s[7 * 33]);
;         NT_STORE(o, (u32x4*)(WT + (size_t)(row0 + n) * K + k0 + 8 * c)); }
	ds_write2_b32 v7, v32, v33 offset1:66
	s_waitcnt vmcnt(60)
	ds_write2_b32 v7, v34, v35 offset0:132 offset1:198
	s_waitcnt vmcnt(58)
	ds_write2_b32 v8, v36, v37 offset0:8 offset1:74
	s_waitcnt vmcnt(56)
	ds_write2_b32 v8, v38, v39 offset0:140 offset1:206
	s_waitcnt vmcnt(54)
	ds_write2_b32 v9, v40, v41 offset1:66
	s_waitcnt vmcnt(52)
	ds_write2_b32 v9, v42, v43 offset0:132 offset1:198
	s_waitcnt vmcnt(50)
	ds_write2_b32 v10, v44, v45 offset0:8 offset1:74
	s_waitcnt vmcnt(48)
	ds_write2_b32 v10, v46, v47 offset0:140 offset1:206
	s_waitcnt vmcnt(46)
	ds_write2_b32 v11, v48, v49 offset1:66
	s_waitcnt vmcnt(44)
	ds_write2_b32 v11, v50, v51 offset0:132 offset1:198
	s_waitcnt vmcnt(42)
	ds_write2_b32 v12, v52, v53 offset0:8 offset1:74
	s_waitcnt vmcnt(40)
	ds_write2_b32 v12, v54, v55 offset0:140 offset1:206
	s_waitcnt vmcnt(38)
	ds_write2_b32 v13, v56, v57 offset1:66
	s_waitcnt vmcnt(36)
	ds_write2_b32 v13, v58, v59 offset0:132 offset1:198
	s_waitcnt vmcnt(34)
	ds_write2_b32 v14, v60, v61 offset0:8 offset1:74
	s_waitcnt vmcnt(32)
	ds_write2_b32 v14, v62, v63 offset0:140 offset1:206
	ds_read2_b32 v[72:73], v15 offset1:8
	ds_read2_b32 v[74:75], v15 offset0:33 offset1:41
	ds_read2_b32 v[76:77], v15 offset0:66 offset1:74
	ds_read2_b32 v[78:79], v15 offset0:99 offset1:107
	ds_read2_b32 v[80:81], v15 offset0:132 offset1:140
	ds_read2_b32 v[82:83], v15 offset0:165 offset1:173
	ds_read2_b32 v[84:85], v15 offset0:198 offset1:206
	ds_read2_b32 v[86:87], v15 offset0:231 offset1:239
	ds_read2_b32 v[88:89], v15 offset0:16 offset1:24
	ds_read2_b32 v[90:91], v15 offset0:49 offset1:57
	ds_read2_b32 v[92:93], v15 offset0:82 offset1:90
	ds_read2_b32 v[94:95], v15 offset0:115 offset1:123
	s_waitcnt lgkmcnt(4)
	v_cvt_pk_bf16_f32 v104, v72, v74
	v_cvt_pk_bf16_f32 v105, v76, v78
	v_cvt_pk_bf16_f32 v106, v80, v82
	v_cvt_pk_bf16_f32 v107, v84, v86
	v_cvt_pk_bf16_f32 v108, v73, v75
	v_cvt_pk_bf16_f32 v109, v77, v79
	v_cvt_pk_bf16_f32 v110, v81, v83
	v_cvt_pk_bf16_f32 v111, v85, v87
	ds_read2_b32 v[96:97], v15 offset0:148 offset1:156
	ds_read2_b32 v[98:99], v15 offset0:181 offset1:189
	ds_read2_b32 v[100:101], v15 offset0:214 offset1:222
	ds_read2_b32 v[102:103], v15 offset0:247 offset1:255
	global_store_dwordx4 v[64:65], v[104:107], off nt
	global_store_dwordx4 v[66:67], v[108:111], off nt
	s_waitcnt lgkmcnt(0)
	v_cvt_pk_bf16_f32 v112, v88, v90
	v_cvt_pk_bf16_f32 v113, v92, v94
	v_cvt_pk_bf16_f32 v114, v96, v98
	v_cvt_pk_bf16_f32 v115, v100, v102
	v_cvt_pk_bf16_f32 v116, v89, v91
	v_cvt_pk_bf16_f32 v117, v93, v95
	v_cvt_pk_bf16_f32 v118, v97, v99
	v_cvt_pk_bf16_f32 v119, v101, v103
	global_store_dwordx4 v[68:69], v[112:115], off nt
	global_store_dwordx4 v[70:71], v[116:119], off nt
	s_waitcnt vmcnt(34)
	ds_write2_b32 v7, v162, v163 offset1:66
	s_waitcnt vmcnt(32)
	ds_write2_b32 v7, v164, v165 offset0:132 offset1:198
	s_waitcnt vmcnt(30)
	ds_write2_b32 v8, v166, v167 offset0:8 offset1:74
	s_waitcnt vmcnt(28)
	ds_write2_b32 v8, v168, v169 offset0:140 offset1:206
	s_waitcnt vmcnt(26)
	ds_write2_b32 v9, v170, v171 offset1:66
	s_waitcnt vmcnt(24)
	ds_write2_b32 v9, v172, v173 offset0:132 offset1:198
	s_waitcnt vmcnt(22)
	ds_write2_b32 v10, v174, v175 offset0:8 offset1:74
	s_waitcnt vmcnt(20)
	ds_write2_b32 v10, v176, v177 offset0:140 offset1:206
	s_waitcnt vmcnt(18)
	ds_write2_b32 v11, v178, v179 offset1:66
	s_waitcnt vmcnt(16)
	ds_write2_b32 v11, v180, v181 offset0:132 offset1:198
	s_waitcnt vmcnt(14)
	ds_write2_b32 v12, v182, v183 offset0:8 offset1:74
	s_waitcnt vmcnt(12)
	ds_write2_b32 v12, v184, v185 offset0:140 offset1:206
	s_waitcnt vmcnt(10)
	ds_write2_b32 v13, v186, v187 offset1:66
	s_waitcnt vmcnt(8)
	ds_write2_b32 v13, v188, v189 offset0:132 offset1:198
	s_waitcnt vmcnt(6)
	ds_write2_b32 v14, v190, v191 offset0:8 offset1:74
	s_waitcnt vmcnt(4)
	ds_write2_b32 v14, v192, v193 offset0:140 offset1:206
	ds_read2_b32 v[72:73], v15 offset1:8
	ds_read2_b32 v[74:75], v15 offset0:33 offset1:41
	ds_read2_b32 v[76:77], v15 offset0:66 offset1:74
	ds_read2_b32 v[78:79], v15 offset0:99 offset1:107
	ds_read2_b32 v[80:81], v15 offset0:132 offset1:140
	ds_read2_b32 v[82:83], v15 offset0:165 offset1:173
	ds_read2_b32 v[84:85], v15 offset0:198 offset1:206
	ds_read2_b32 v[86:87], v15 offset0:231 offset1:239
	ds_read2_b32 v[88:89], v15 offset0:16 offset1:24
	ds_read2_b32 v[90:91], v15 offset0:49 offset1:57
	ds_read2_b32 v[92:93], v15 offset0:82 offset1:90
	ds_read2_b32 v[94:95], v15 offset0:115 offset1:123
	s_waitcnt lgkmcnt(4)
	v_cvt_pk_bf16_f32 v104, v72, v74
	v_cvt_pk_bf16_f32 v105, v76, v78
	v_cvt_pk_bf16_f32 v106, v80, v82
	v_cvt_pk_bf16_f32 v107, v84, v86
	v_cvt_pk_bf16_f32 v108, v73, v75
	v_cvt_pk_bf16_f32 v109, v77, v79
	v_cvt_pk_bf16_f32 v110, v81, v83
	v_cvt_pk_bf16_f32 v111, v85, v87
	ds_read2_b32 v[96:97], v15 offset0:148 offset1:156
	ds_read2_b32 v[98:99], v15 offset0:181 offset1:189
	ds_read2_b32 v[100:101], v15 offset0:214 offset1:222
	ds_read2_b32 v[102:103], v15 offset0:247 offset1:255
	global_store_dwordx4 v[126:127], v[104:107], off nt
	global_store_dwordx4 v[128:129], v[108:111], off nt
	s_waitcnt lgkmcnt(0)
	v_cvt_pk_bf16_f32 v112, v88, v90
	v_cvt_pk_bf16_f32 v113, v92, v94
	v_cvt_pk_bf16_f32 v114, v96, v98
	v_cvt_pk_bf16_f32 v115, v100, v102
	v_cvt_pk_bf16_f32 v116, v89, v91
	v_cvt_pk_bf16_f32 v117, v93, v95
	v_cvt_pk_bf16_f32 v118, v97, v99
	v_cvt_pk_bf16_f32 v119, v101, v103
	global_store_dwordx4 v[130:131], v[112:115], off nt
	global_store_dwordx4 v[132:133], v[116:119], off nt
	s_add_i32 s2, s2, 0x180
	s_cmp_lt_u32 s2, 0x8000
	s_cbranch_scc1 .Lsh_gu_loop
